# P7 (down GEMM) walks the row panels in reverse order so it reads the most recently written part of U first (memory-side cache locality)
# speedup vs baseline: 1.0060x; 1.0060x over previous
.LBB0_1057:
	s_ashr_i32 s10, s12, 3
	s_add_i32 s10, s15, s10
	s_ashr_i32 s11, s10, 31
	s_lshr_b32 s11, s11, 27
	s_add_i32 s11, s10, s11
	s_ashr_i32 s12, s11, 5
	s_and_b32 s11, s11, 0xffe0
	s_sub_i32 s10, s10, s11
	s_bfe_i32 s11, s10, 0x80000
	s_bfe_u32 s11, s11, 0x3000c
	s_add_i32 s11, s10, s11
	s_and_b32 s13, s11, 0xf8
	s_sub_i32 s10, s10, s13
	s_lshl_b32 s12, s12, 3
	s_sext_i32_i8 s10, s10
	s_add_i32 s26, s12, s10
	s_sub_i32 s26, 0x7f, s26
	s_bfe_i32 s10, s11, 0x80000
	s_sext_i32_i16 s10, s10
	s_ashr_i32 s28, s10, 3

.LBB0_1070:
	s_ashr_i32 s16, s18, 3
	s_add_i32 s16, s20, s16
	s_ashr_i32 s17, s16, 31
	s_lshr_b32 s17, s17, 27
	s_add_i32 s17, s16, s17
	s_ashr_i32 s18, s17, 5
	s_lshl_b32 s18, s18, 3
	s_sub_i32 s19, 0x80, s18
	s_min_i32 s19, s19, 8
	s_abs_i32 s20, s19
	v_cvt_f32_u32_e32 v1, s20
	s_sub_i32 s22, 0, s20
	s_andn2_b32 s17, s17, 31
	s_sub_i32 s17, s16, s17
	v_rcp_iflag_f32_e32 v1, v1
	s_abs_i32 s16, s17
	s_xor_b32 s21, s17, s19
	s_ashr_i32 s21, s21, 31
	v_mul_f32_e32 v1, 0x4f7ffffe, v1
	v_cvt_u32_f32_e32 v1, v1
	s_nop 0
	v_readfirstlane_b32 s23, v1
	s_mul_i32 s22, s22, s23
	s_mul_hi_u32 s22, s23, s22
	s_add_i32 s23, s23, s22
	s_mul_hi_u32 s22, s16, s23
	s_mul_i32 s23, s22, s20
	s_sub_i32 s16, s16, s23
	s_add_i32 s24, s22, 1
	s_sub_i32 s23, s16, s20
	s_cmp_ge_u32 s16, s20
	s_cselect_b32 s22, s24, s22
	s_cselect_b32 s16, s23, s16
	s_add_i32 s23, s22, 1
	s_cmp_ge_u32 s16, s20
	s_cselect_b32 s16, s23, s22
	s_xor_b32 s16, s16, s21
	s_sub_i32 s16, s16, s21
	s_mul_i32 s19, s16, s19
	s_sub_i32 s17, s17, s19
	s_add_i32 s18, s18, s17
	s_sub_i32 s18, 0x7f, s18
	s_mov_b64 s[22:23], -1
